# post_rows: all per-row loads issued together at iteration top (4 serialized load stages -> 1), gain loads hoisted out of the loop
# speedup vs baseline: 1.0048x; 1.0007x over previous
; __device__ __forceinline__ float fexp2(float x) { return __builtin_amdgcn_exp2f(x); }
; __device__ __forceinline__ float frcp(float x) { return __builtin_amdgcn_rcpf(x); }
; __device__ __forceinline__ void post_rows(const bf16_t* OP, const float* LSE, const bf16_t* zC, bf16_t* yb, bf16_t* yc, const float* hnorm, int tid, int bid, int nbk) {
;     const int lane = tid & 63, wv = tid >> 6;
;     const int gw = bid * 8 + wv, NGW = nbk * 8;
;     for (int r = gw; r < MH; r += NGW) {
;         {
;             const int hb = lane >> 3;
;             const float l0 = LSE[((size_t)0 * MH + r) * 8 + hb], l1 = LSE[((size_t)1 * MH + r) * 8 + hb], l2 = LSE[((size_t)2 * MH + r) * 8 + hb];
;             const float mx = fmaxf(l0, fmaxf(l1, l2));
;             float w0 = fexp2(l0 - mx), w1 = fexp2(l1 - mx), w2 = fexp2(l2 - mx);
;             const float iw = frcp(w0 + w1 + w2); w0 *= iw; w1 *= iw; w2 *= iw;
;             const u32x4 a = *(const u32x4*)(OP + ((size_t)0 * MH + r) * 512 + lane * 8), b = *(const u32x4*)(OP + ((size_t)1 * MH + r) * 512 + lane * 8), c = *(const u32x4*)(OP + ((size_t)2 * MH + r) * 512 + lane * 8);
.LBB0_151:
	s_andn2_b64 vcc, exec, s[40:41]
	s_cbranch_vccnz .LBB0_156
	v_ashrrev_i32_e32 v4, 6, v187
	s_lshl_b32 s40, s11, 3
	v_add_u32_e32 v3, s40, v4
	s_movk_i32 s14, 0x4000
	v_cmp_gt_i32_e32 vcc, s14, v3
	s_and_saveexec_b64 s[42:43], vcc
	s_cbranch_execz .LBB0_155
	v_and_b32_e32 v1, 64, v178
	v_xor_b32_e32 v0, 1, v178
	v_add_u32_e32 v1, 64, v1
	v_cmp_lt_i32_e32 vcc, v0, v1
	s_load_dwordx2 s[14:15], s[0:1], 0x68
	v_readlane_b32 s12, v255, 31
	v_cndmask_b32_e32 v0, v178, v0, vcc
	s_waitcnt vmcnt(7)
	v_lshlrev_b32_e32 v16, 2, v0
	v_xor_b32_e32 v0, 2, v178
	v_cmp_lt_i32_e32 vcc, v0, v1
	s_lshl_b32 s48, s12, 7
	s_ashr_i32 s49, s48, 31
	v_cndmask_b32_e32 v0, v178, v0, vcc
	v_lshlrev_b32_e32 v17, 2, v0
	v_xor_b32_e32 v0, 4, v178
	v_cmp_lt_i32_e32 vcc, v0, v1
	s_lshl_b32 s46, s10, 3
	s_lshl_b64 s[48:49], s[48:49], 2
	v_cndmask_b32_e32 v0, v178, v0, vcc
	v_lshlrev_b32_e32 v18, 2, v0
	v_xor_b32_e32 v0, 8, v178
	v_cmp_lt_i32_e32 vcc, v0, v1
	s_waitcnt lgkmcnt(0)
	s_add_u32 s14, s14, s48
	s_addc_u32 s15, s15, s49
	v_cndmask_b32_e32 v0, v178, v0, vcc
	v_lshlrev_b32_e32 v19, 2, v0
	v_lshlrev_b32_e32 v0, 5, v187
	v_ashrrev_i32_e32 v5, 31, v4
	s_ashr_i32 s41, s40, 31
	v_and_b32_e32 v0, 0x1e0, v0
	v_mov_b32_e32 v1, v2
	v_lshl_add_u64 v[4:5], v[4:5], 0, s[40:41]
	v_lshl_add_u64 v[0:1], s[14:15], 0, v[0:1]
	v_mad_u64_u32 v[6:7], s[14:15], v4, s8, 0
	v_mad_i32_i24 v9, v5, s8, v7
	v_lshlrev_b32_e32 v7, 4, v187
	v_and_b32_e32 v14, 0x3f0, v7
	s_waitcnt vmcnt(6)
	v_and_b32_e32 v20, 56, v187
	v_or_b32_e32 v8, v6, v14
	v_mad_u64_u32 v[6:7], s[14:15], v4, s9, 0
	v_lshlrev_b64 v[12:13], 10, v[4:5]
	s_ashr_i32 s47, s46, 31
	v_or_b32_e32 v10, v6, v14
	v_or_b32_e32 v12, v12, v14
	v_lshlrev_b64 v[14:15], 5, v[4:5]
	v_lshrrev_b32_e32 v4, 1, v20
	s_mul_i32 s48, s10, 0xa000
	s_mul_hi_i32 s49, s46, 0x1400
	v_mad_i32_i24 v11, v5, s9, v7
	s_mul_i32 s50, s10, 0x6000
	s_mul_hi_i32 s51, s46, 0xc00
	s_lshl_b64 s[52:53], s[46:47], 10
	v_or_b32_e32 v14, v14, v4
	s_lshl_b64 s[54:55], s[46:47], 5
	s_mov_b64 s[56:57], 0
	v_readlane_b32 s13, v255, 32
	global_load_dwordx4 v[216:219], v[0:1], off offset:16
	global_load_dwordx4 v[220:223], v[0:1], off
	s_waitcnt vmcnt(0)
.LBB0_154:
	v_lshl_add_u64 v[224:225], s[60:61], 0, v[14:15]
	v_lshl_add_u64 v[226:227], s[60:61], 0, v[12:13]
	v_lshl_add_u64 v[228:229], s[60:61], 0, v[8:9]
	v_add_co_u32_e32 v230, vcc, 0x1e800000, v224
	s_nop 1
	v_addc_co_u32_e32 v231, vcc, 0, v225, vcc
	v_add_co_u32_e32 v232, vcc, 0x1e880000, v224
	s_nop 1
	v_addc_co_u32_e32 v233, vcc, 0, v225, vcc
	v_add_co_u32_e32 v234, vcc, 0x1e900000, v224
	s_nop 1
	v_addc_co_u32_e32 v235, vcc, 0, v225, vcc
	global_load_dword v188, v[230:231], off
	global_load_dword v189, v[232:233], off
	global_load_dword v190, v[234:235], off
	v_add_co_u32_e32 v230, vcc, 0x1b800000, v226
	s_nop 1
	v_addc_co_u32_e32 v231, vcc, 0, v227, vcc
	v_add_co_u32_e32 v232, vcc, 0x1c800000, v226
	s_nop 1
	v_addc_co_u32_e32 v233, vcc, 0, v227, vcc
	v_add_co_u32_e32 v234, vcc, 0x1d800000, v226
	s_nop 1
	v_addc_co_u32_e32 v235, vcc, 0, v227, vcc
	global_load_dwordx4 v[192:195], v[230:231], off
	global_load_dwordx4 v[196:199], v[232:233], off
	global_load_dwordx4 v[200:203], v[234:235], off
	v_add_co_u32_e32 v230, vcc, 0xd800000, v228
	s_nop 1
	v_addc_co_u32_e32 v231, vcc, 0, v229, vcc
	v_add_co_u32_e32 v232, vcc, 0xd801000, v228
	s_nop 1
	v_addc_co_u32_e32 v233, vcc, 0, v229, vcc
	global_load_dwordx4 v[204:207], v[230:231], off offset:1024
	global_load_dwordx4 v[208:211], v[230:231], off offset:2048
	global_load_dwordx4 v[212:215], v[232:233], off
	v_lshl_add_u64 v[4:5], s[60:61], 0, v[14:15]
	v_add_co_u32_e32 v6, vcc, 0x1e800000, v4
	v_lshl_add_u64 v[24:25], s[60:61], 0, v[12:13]
	v_addc_co_u32_e32 v7, vcc, 0, v5, vcc
	v_add_co_u32_e32 v6, vcc, 0x1e880000, v4
	s_mov_b32 s14, 0x1b800000
	s_nop 0
	v_addc_co_u32_e32 v7, vcc, 0, v5, vcc
	v_add_co_u32_e32 v4, vcc, 0x1e900000, v4
	s_nop 0
	v_addc_co_u32_e32 v5, vcc, 0, v5, vcc
	v_add_u32_e32 v3, s46, v3
	v_lshl_add_u64 v[12:13], v[12:13], 0, s[52:53]
	v_lshl_add_u64 v[14:15], v[14:15], 0, s[54:55]
	s_waitcnt vmcnt(6)
	v_mov_b32_e32 v20, v188
	v_mov_b32_e32 v6, v189
	v_mov_b32_e32 v4, v190
	v_max3_f32 v5, v20, v6, v4
	v_sub_f32_e32 v7, v20, v5
	v_sub_f32_e32 v6, v6, v5
	v_exp_f32_e32 v29, v7
	v_exp_f32_e32 v28, v6
	v_sub_f32_e32 v4, v4, v5
	v_exp_f32_e32 v4, v4
	v_add_f32_e32 v5, v29, v28
	v_add_f32_e32 v5, v4, v5
	v_rcp_f32_e32 v30, v5
	s_nop 0
	v_mul_f32_e32 v32, v4, v30
	v_add_co_u32_e32 v4, vcc, s14, v24
	s_mov_b32 s14, 0x1c800000
	s_nop 0
	v_addc_co_u32_e32 v5, vcc, 0, v25, vcc
	v_add_co_u32_e32 v20, vcc, s14, v24
	s_mov_b32 s14, 0x1d800000
	s_nop 0
	v_addc_co_u32_e32 v21, vcc, 0, v25, vcc
	s_waitcnt vmcnt(3)
; __device__ __forceinline__ unsigned pk2(float lo, float hi) { f32x2 v = {lo, hi}; bf16x2_t b = __builtin_convertvector(v, bf16x2_t); return __builtin_bit_cast(unsigned, b); }
; __device__ __forceinline__ float bflo(unsigned w) { return __uint_as_float(w << 16); }
; __device__ __forceinline__ float bfhi(unsigned w) { return __uint_as_float(w & 0xffff0000u); }
; __device__ __forceinline__ void post_rows(const bf16_t* OP, const float* LSE, const bf16_t* zC, bf16_t* yb, bf16_t* yc, const float* hnorm, int tid, int bid, int nbk) {
;     ...
;             const u32x4 a = *(const u32x4*)(OP + ((size_t)0 * MH + r) * 512 + lane * 8), b = *(const u32x4*)(OP + ((size_t)1 * MH + r) * 512 + lane * 8), c = *(const u32x4*)(OP + ((size_t)2 * MH + r) * 512 + lane * 8);
;             u32x4 o;
;             o.x = pk2(w0 * bflo(a.x) + w1 * bflo(b.x) + w2 * bflo(c.x), w0 * bfhi(a.x) + w1 * bfhi(b.x) + w2 * bfhi(c.x));
;             o.y = pk2(w0 * bflo(a.y) + w1 * bflo(b.y) + w2 * bflo(c.y), w0 * bfhi(a.y) + w1 * bfhi(b.y) + w2 * bfhi(c.y));
;             o.z = pk2(w0 * bflo(a.z) + w1 * bflo(b.z) + w2 * bflo(c.z), w0 * bfhi(a.z) + w1 * bfhi(b.z) + w2 * bfhi(c.z));
;             o.w = pk2(w0 * bflo(a.w) + w1 * bflo(b.w) + w2 * bflo(c.w), w0 * bfhi(a.w) + w1 * bfhi(b.w) + w2 * bfhi(c.w));
;             *(u32x4*)(yb + (size_t)r * 1536 + lane * 8) = o;
	v_mov_b32_e32 v4, v192
	v_mov_b32_e32 v5, v193
	v_mov_b32_e32 v6, v194
	v_mov_b32_e32 v7, v195
	v_add_co_u32_e32 v24, vcc, s14, v24
	v_mov_b32_e32 v20, v196
	v_mov_b32_e32 v21, v197
	v_mov_b32_e32 v22, v198
	v_mov_b32_e32 v23, v199
	s_nop 0
	v_addc_co_u32_e32 v25, vcc, 0, v25, vcc
	v_mov_b32_e32 v24, v200
	v_mov_b32_e32 v25, v201
	v_mov_b32_e32 v26, v202
	v_mov_b32_e32 v27, v203
	v_pk_mul_f32 v[28:29], v[28:29], v[30:31] op_sel_hi:[1,0]
	s_mov_b32 s14, 0x18800000
	v_lshlrev_b32_e32 v34, 16, v4
	v_and_b32_e32 v31, 0xffff0000, v4
	v_and_b32_e32 v35, 0xffff0000, v20
	v_lshlrev_b32_e32 v30, 16, v20
	v_pk_mul_f32 v[34:35], v[28:29], v[34:35] op_sel:[1,0] op_sel_hi:[0,1]
	v_lshlrev_b32_e32 v36, 16, v24
	v_and_b32_e32 v37, 0xffff0000, v24
	v_pk_fma_f32 v[30:31], v[28:29], v[30:31], v[34:35]
	v_lshlrev_b32_e32 v20, 16, v5
	v_pk_fma_f32 v[30:31], v[32:33], v[36:37], v[30:31] op_sel_hi:[0,1,1]
	v_cvt_pk_bf16_f32 v4, v30, v31
	v_lshlrev_b32_e32 v30, 16, v21
	v_and_b32_e32 v21, 0xffff0000, v21
	v_and_b32_e32 v31, 0xffff0000, v5
	v_pk_mul_f32 v[20:21], v[28:29], v[20:21] op_sel:[1,0] op_sel_hi:[0,1]
	v_lshlrev_b32_e32 v24, 16, v25
	v_and_b32_e32 v25, 0xffff0000, v25
	v_pk_fma_f32 v[20:21], v[28:29], v[30:31], v[20:21]
	v_lshlrev_b32_e32 v30, 16, v26
	v_pk_fma_f32 v[20:21], v[32:33], v[24:25], v[20:21] op_sel_hi:[0,1,1]
	v_lshlrev_b32_e32 v24, 16, v6
	v_and_b32_e32 v25, 0xffff0000, v22
	v_cvt_pk_bf16_f32 v5, v20, v21
	v_lshlrev_b32_e32 v20, 16, v22
	v_and_b32_e32 v21, 0xffff0000, v6
	v_pk_mul_f32 v[24:25], v[28:29], v[24:25] op_sel:[1,0] op_sel_hi:[0,1]
	v_and_b32_e32 v31, 0xffff0000, v26
	v_pk_fma_f32 v[20:21], v[28:29], v[20:21], v[24:25]
	v_lshlrev_b32_e32 v22, 16, v7
	v_pk_fma_f32 v[20:21], v[32:33], v[30:31], v[20:21] op_sel_hi:[0,1,1]
	v_cvt_pk_bf16_f32 v6, v20, v21
	v_lshlrev_b32_e32 v20, 16, v23
	v_and_b32_e32 v23, 0xffff0000, v23
	v_and_b32_e32 v21, 0xffff0000, v7
	v_pk_mul_f32 v[22:23], v[28:29], v[22:23] op_sel:[1,0] op_sel_hi:[0,1]
	v_pk_fma_f32 v[20:21], v[28:29], v[20:21], v[22:23]
	v_lshlrev_b32_e32 v22, 16, v27
	v_and_b32_e32 v23, 0xffff0000, v27
	v_pk_fma_f32 v[20:21], v[32:33], v[22:23], v[20:21] op_sel_hi:[0,1,1]
	v_cvt_pk_bf16_f32 v7, v20, v21
	v_lshl_add_u64 v[20:21], s[60:61], 0, v[10:11]
	v_add_co_u32_e32 v34, vcc, s14, v20
	v_lshl_add_u64 v[24:25], s[60:61], 0, v[8:9]
	s_nop 0
	v_addc_co_u32_e32 v35, vcc, 0, v21, vcc
	s_mov_b32 s14, 0xd800000
	v_add_co_u32_e32 v20, vcc, s14, v24
	s_mov_b32 s14, 0xd801000
	s_nop 0
	v_addc_co_u32_e32 v21, vcc, 0, v25, vcc
	global_store_dwordx4 v[34:35], v[4:7], off offset:1024
	v_add_co_u32_e32 v24, vcc, s14, v24
	s_nop 1
	s_waitcnt vmcnt(1)
; __device__ __forceinline__ unsigned pk2(float lo, float hi) { f32x2 v = {lo, hi}; bf16x2_t b = __builtin_convertvector(v, bf16x2_t); return __builtin_bit_cast(unsigned, b); }
; __device__ __forceinline__ float bflo(unsigned w) { return __uint_as_float(w << 16); }
; __device__ __forceinline__ float bfhi(unsigned w) { return __uint_as_float(w & 0xffff0000u); }
; __device__ __forceinline__ float siluf_(float x) { return x * frcp(1.f + fexp2(-LOG2E * x)); }
; __device__ __forceinline__ void post_rows(const bf16_t* OP, const float* LSE, const bf16_t* zC, bf16_t* yb, bf16_t* yc, const float* hnorm, int tid, int bid, int nbk) {
;     ...
;         {
;             const bf16_t* zr = zC + (size_t)r * 2560 + lane * 8;
;             const u32x4 a = *(const u32x4*)(zr + 512), b = *(const u32x4*)(zr + 1024), g = *(const u32x4*)(zr + 2048);
;             float s[8], og[8];
;             s[0] = bflo(a.x) + bflo(b.x); s[1] = bfhi(a.x) + bfhi(b.x); s[2] = bflo(a.y) + bflo(b.y); s[3] = bfhi(a.y) + bfhi(b.y);
;             s[4] = bflo(a.z) + bflo(b.z); s[5] = bfhi(a.z) + bfhi(b.z); s[6] = bflo(a.w) + bflo(b.w); s[7] = bfhi(a.w) + bfhi(b.w);
;             og[0] = bflo(g.x); og[1] = bfhi(g.x); og[2] = bflo(g.y); og[3] = bfhi(g.y); og[4] = bflo(g.z); og[5] = bfhi(g.z); og[6] = bflo(g.w); og[7] = bfhi(g.w);
;             float ss = 0.f;
; #pragma unroll
;             for (int i = 0; i < 8; ++i) ss += s[i] * s[i];
;             ss += __shfl_xor(ss, 1); ss += __shfl_xor(ss, 2); ss += __shfl_xor(ss, 4); ss += __shfl_xor(ss, 8);
;             const float rn = 1.0f / sqrtf(ss * (1.f / 128.f) + 1e-6f);
;             const float* gn = hnorm + (lane & 15) * 8;
;             float y[8];
; #pragma unroll
;             for (int i = 0; i < 8; ++i) y[i] = s[i] * rn * gn[i] * siluf_(og[i]);
;             u32x4 o; o.x = pk2(y[0], y[1]); o.y = pk2(y[2], y[3]); o.z = pk2(y[4], y[5]); o.w = pk2(y[6], y[7]);
;             *(u32x4*)(yc + (size_t)r * 1536 + lane * 8) = o;
;         }
	v_mov_b32_e32 v4, v204
	v_mov_b32_e32 v5, v205
	v_mov_b32_e32 v6, v206
	v_mov_b32_e32 v7, v207
	s_nop 0
	v_mov_b32_e32 v20, v208
	v_mov_b32_e32 v21, v209
	v_mov_b32_e32 v22, v210
	v_mov_b32_e32 v23, v211
	v_addc_co_u32_e32 v25, vcc, 0, v25, vcc
	v_mov_b32_e32 v24, v212
	v_mov_b32_e32 v25, v213
	v_mov_b32_e32 v26, v214
	v_mov_b32_e32 v27, v215
	v_lshl_add_u64 v[8:9], v[8:9], 0, s[48:49]
	v_lshl_add_u64 v[10:11], v[10:11], 0, s[50:51]
	v_lshlrev_b32_e32 v28, 16, v7
	v_and_b32_e32 v29, 0xffff0000, v7
	v_lshlrev_b32_e32 v30, 16, v23
	v_and_b32_e32 v31, 0xffff0000, v23
	v_pk_add_f32 v[36:37], v[28:29], v[30:31]
	v_lshlrev_b32_e32 v28, 16, v6
	v_and_b32_e32 v29, 0xffff0000, v6
	v_lshlrev_b32_e32 v6, 16, v22
	v_and_b32_e32 v7, 0xffff0000, v22
	v_lshlrev_b32_e32 v22, 16, v26
	v_and_b32_e32 v23, 0xffff0000, v26
	v_mul_f32_e32 v26, 0xbfb8aa3b, v22
	v_mul_f32_e32 v45, 0xbfb8aa3b, v23
	v_exp_f32_e32 v26, v26
	v_exp_f32_e32 v45, v45
	v_lshlrev_b32_e32 v46, 16, v21
	v_and_b32_e32 v47, 0xffff0000, v21
	v_add_f32_e32 v26, 1.0, v26
	v_add_f32_e32 v45, 1.0, v45
	v_rcp_f32_e32 v44, v26
	v_rcp_f32_e32 v45, v45
	v_lshlrev_b32_e32 v38, 16, v27
	v_and_b32_e32 v39, 0xffff0000, v27
	v_pk_add_f32 v[6:7], v[28:29], v[6:7]
	v_pk_mul_f32 v[22:23], v[44:45], v[22:23]
	v_lshlrev_b32_e32 v44, 16, v5
	v_and_b32_e32 v45, 0xffff0000, v5
	v_pk_add_f32 v[44:45], v[44:45], v[46:47]
	v_lshlrev_b32_e32 v46, 16, v25
	v_mul_f32_e32 v5, 0xbfb8aa3b, v46
	v_mov_b32_e32 v26, v216
	v_mov_b32_e32 v27, v217
	v_mov_b32_e32 v28, v218
	v_mov_b32_e32 v29, v219
	v_mov_b32_e32 v30, v220
	v_mov_b32_e32 v31, v221
	v_mov_b32_e32 v32, v222
	v_mov_b32_e32 v33, v223
	v_exp_f32_e32 v5, v5
	v_and_b32_e32 v47, 0xffff0000, v25
	v_and_b32_e32 v21, 0xffff0000, v24
	v_pk_mul_f32 v[48:49], v[44:45], v[44:45]
	v_add_f32_e32 v5, 1.0, v5
	v_rcp_f32_e32 v50, v5
	v_mul_f32_e32 v5, 0xbfb8aa3b, v47
	v_exp_f32_e32 v5, v5
	v_pk_mul_f32 v[42:43], v[6:7], v[6:7]
	v_pk_mul_f32 v[40:41], v[36:37], v[36:37]
	v_add_f32_e32 v5, 1.0, v5
	v_rcp_f32_e32 v51, v5
	v_and_b32_e32 v5, 0xffff0000, v20
	v_pk_mul_f32 v[46:47], v[50:51], v[46:47]
	v_lshlrev_b32_e32 v50, 16, v4
	v_and_b32_e32 v51, 0xffff0000, v4
	v_lshlrev_b32_e32 v4, 16, v20
	v_pk_add_f32 v[4:5], v[50:51], v[4:5]
	v_lshlrev_b32_e32 v20, 16, v24
	v_pk_mul_f32 v[24:25], v[4:5], v[4:5]
	v_mul_f32_e32 v50, 0xbfb8aa3b, v20
	v_add_f32_e32 v24, v24, v25
	v_add_f32_e32 v24, v48, v24
	v_add_f32_e32 v24, v49, v24
	v_add_f32_e32 v24, v42, v24
	v_add_f32_e32 v24, v43, v24
	v_add_f32_e32 v24, v40, v24
	v_add_f32_e32 v24, v41, v24
	ds_bpermute_b32 v25, v16, v24
	v_mul_f32_e32 v51, 0xbfb8aa3b, v21
	v_exp_f32_e32 v50, v50
	v_exp_f32_e32 v51, v51
	s_waitcnt lgkmcnt(0)
	v_add_f32_e32 v24, v24, v25
	ds_bpermute_b32 v25, v17, v24
	v_add_f32_e32 v50, 1.0, v50
	v_add_f32_e32 v51, 1.0, v51
	v_rcp_f32_e32 v50, v50
	v_rcp_f32_e32 v51, v51
	s_waitcnt lgkmcnt(0)
	v_add_f32_e32 v24, v24, v25
	ds_bpermute_b32 v25, v18, v24
	v_pk_mul_f32 v[20:21], v[50:51], v[20:21]
	s_waitcnt lgkmcnt(0)
	v_add_f32_e32 v24, v24, v25
	ds_bpermute_b32 v25, v19, v24
	s_waitcnt lgkmcnt(0)
	v_add_f32_e32 v24, v24, v25
	v_fmamk_f32 v24, v24, 0x3c000000, v175
	v_cmp_gt_f32_e32 vcc, s33, v24
	v_mul_f32_e32 v25, 0x4f800000, v24
	s_nop 0
	v_cndmask_b32_e32 v24, v24, v25, vcc
	v_sqrt_f32_e32 v25, v24
	s_nop 0
	v_add_u32_e32 v40, -1, v25
	v_fma_f32 v41, -v40, v25, v24
	v_cmp_ge_f32_e64 s[40:41], 0, v41
	v_add_u32_e32 v41, 1, v25
	s_nop 0
	v_cndmask_b32_e64 v40, v25, v40, s[40:41]
	v_fma_f32 v25, -v41, v25, v24
	v_cmp_lt_f32_e64 s[40:41], 0, v25
	s_nop 1
	v_cndmask_b32_e64 v25, v40, v41, s[40:41]
	v_mul_f32_e32 v40, 0x37800000, v25
	v_cndmask_b32_e32 v25, v25, v40, vcc
	v_cmp_class_f32_e32 vcc, v24, v180
	s_nop 1
	v_cndmask_b32_e32 v24, v25, v24, vcc
	v_div_scale_f32 v25, s[14:15], v24, v24, 1.0
	v_rcp_f32_e32 v40, v25
	s_movk_i32 s14, 0x3fff
	v_fma_f32 v41, -v25, v40, 1.0
	v_fmac_f32_e32 v40, v41, v40
	v_div_scale_f32 v41, vcc, 1.0, v24, 1.0
	v_mul_f32_e32 v42, v41, v40
	v_fma_f32 v43, -v25, v42, v41
	v_fmac_f32_e32 v42, v43, v40
	v_fma_f32 v25, -v25, v42, v41
	v_div_fmas_f32 v25, v25, v40, v42
	v_div_fixup_f32 v24, v25, v24, 1.0
	v_pk_mul_f32 v[6:7], v[6:7], v[24:25] op_sel_hi:[1,0]
	v_pk_mul_f32 v[4:5], v[4:5], v[24:25] op_sel_hi:[1,0]
	v_pk_mul_f32 v[6:7], v[26:27], v[6:7]
	v_pk_mul_f32 v[4:5], v[30:31], v[4:5]
	v_pk_mul_f32 v[6:7], v[22:23], v[6:7]
	v_mul_f32_e32 v22, 0xbfb8aa3b, v38
	v_mul_f32_e32 v23, 0xbfb8aa3b, v39
	v_exp_f32_e32 v22, v22
	v_exp_f32_e32 v23, v23
	v_pk_mul_f32 v[4:5], v[20:21], v[4:5]
	v_pk_mul_f32 v[20:21], v[44:45], v[24:25] op_sel_hi:[1,0]
	v_add_f32_e32 v22, 1.0, v22
	v_add_f32_e32 v23, 1.0, v23
	v_rcp_f32_e32 v22, v22
	v_rcp_f32_e32 v23, v23
	v_pk_mul_f32 v[24:25], v[36:37], v[24:25] op_sel_hi:[1,0]
	v_pk_mul_f32 v[20:21], v[32:33], v[20:21]
	v_pk_mul_f32 v[24:25], v[28:29], v[24:25]
	v_pk_mul_f32 v[22:23], v[22:23], v[38:39]
	v_pk_mul_f32 v[20:21], v[46:47], v[20:21]
	v_pk_mul_f32 v[22:23], v[22:23], v[24:25]
	v_cmp_lt_i32_e32 vcc, s14, v3
	v_cvt_pk_bf16_f32 v4, v4, v5
	v_cvt_pk_bf16_f32 v5, v20, v21
	v_cvt_pk_bf16_f32 v6, v6, v7
	v_cvt_pk_bf16_f32 v7, v22, v23
	s_or_b64 s[56:57], vcc, s[56:57]
	global_store_dwordx4 v[34:35], v[4:7], off offset:2048
	s_andn2_b64 exec, exec, s[56:57]
	s_cbranch_execnz .LBB0_154
